# speedup vs baseline: 1.0419x; 1.0006x over previous
; DI unsigned pk2(float lo, float hi) { const f32x2 v = {lo, hi}; return __builtin_bit_cast(unsigned, __builtin_convertvector(v, bf16x2_t)); }
; DI void mixer_tile(unsigned char* smem_, const Params& p, int layer, const bf16_t* __restrict__ proj, bf16_t* __restrict__ y, int tile_) {
;     ...
;         const int g = tid >> 6, win = 2 << g;
;         const int l31 = lane & 31, hi = lane >> 5;
;         const float* pw = p.in[6] + ((size_t)(layer * 4 + g) * 64) * 64;
;         bf16x8 wf[2][4];
; #pragma unroll
;         for (int eh = 0; eh < 2; ++eh)
; #pragma unroll
;             for (int kk = 0; kk < 4; ++kk) {
;                 const float* wp = pw + (size_t)(16 * kk + 8 * hi) * 64 + 32 * eh + l31;
;                 u32x4 w; w.x = pk2(wp[0], wp[64]); w.y = pk2(wp[128], wp[192]); w.z = pk2(wp[256], wp[320]); w.w = pk2(wp[384], wp[448]);
;                 wf[eh][kk] = __builtin_bit_cast(bf16x8, w);
;             }
.LBB0_178:
	s_or_b64 exec, exec, s[0:1]
	v_lshrrev_b32_sdwa v73, v208, v68 dst_sel:DWORD dst_unused:UNUSED_PAD src0_sel:DWORD src1_sel:BYTE_0
	v_or_b32_e32 v0, s16, v73
	v_ashrrev_i32_e32 v1, 31, v0
	v_readlane_b32 s36, v252, 2
	v_lshlrev_b64 v[0:1], 14, v[0:1]
	v_readlane_b32 s48, v252, 14
	v_readlane_b32 s49, v252, 15
	v_lshrrev_b32_e32 v69, 5, v26
	v_lshlrev_b32_e32 v2, 2, v67
	v_lshl_add_u64 v[0:1], s[48:49], 0, v[0:1]
	v_mov_b32_e32 v3, v129
	v_lshl_add_u64 v[4:5], v[0:1], 0, v[2:3]
	v_lshlrev_b32_e32 v6, 11, v69
	v_mov_b32_e32 v7, v129
	v_lshl_add_u64 v[12:13], v[4:5], 0, v[6:7]
	s_waitcnt lgkmcnt(0)
	s_barrier
	global_load_dword v0, v[12:13], off
	global_load_dword v18, v[12:13], off offset:256
	v_or_b32_e32 v14, 0x1000, v6
	v_mov_b32_e32 v15, v129
	v_lshl_add_u64 v[8:9], v[4:5], 0, v[14:15]
	v_mov_b32_e32 v11, v129
	v_cmp_lt_u32_sdwa s[0:1], v68, v209 src0_sel:BYTE_0 src1_sel:DWORD
	s_movk_i32 s2, 0x7f
	v_cmp_gt_u32_sdwa vcc, v68, s2 src0_sel:BYTE_0 src1_sel:DWORD
	v_cmp_eq_u32_e64 s[2:3], 3, v73
	v_lshlrev_b32_e64 v71, v73, 2
	s_or_b32 s20, s18, 1
	v_readlane_b32 s37, v252, 3
	v_readlane_b32 s38, v252, 4
	v_readlane_b32 s39, v252, 5
	v_readlane_b32 s40, v252, 6
	v_readlane_b32 s41, v252, 7
	v_readlane_b32 s42, v252, 8
	v_readlane_b32 s43, v252, 9
	v_readlane_b32 s44, v252, 10
	v_readlane_b32 s45, v252, 11
	v_readlane_b32 s46, v252, 12
	v_readlane_b32 s47, v252, 13
	v_readlane_b32 s50, v252, 16
	v_readlane_b32 s51, v252, 17
	global_load_dword v1, v[12:13], off offset:512
	global_load_dword v19, v[12:13], off offset:768
	global_load_dword v2, v[12:13], off offset:1024
	global_load_dword v20, v[12:13], off offset:1280
	global_load_dword v3, v[12:13], off offset:1536
	global_load_dword v21, v[12:13], off offset:1792
	global_load_dword v32, v[8:9], off
	global_load_dword v22, v[8:9], off offset:256
	global_load_dword v33, v[8:9], off offset:512
	global_load_dword v23, v[8:9], off offset:768
	global_load_dword v34, v[8:9], off offset:1024
	global_load_dword v24, v[8:9], off offset:1280
	global_load_dword v35, v[8:9], off offset:1536
	s_nop 0
	global_load_dword v25, v[8:9], off offset:1792
	v_or_b32_e32 v10, 0x2000, v6
	v_lshl_add_u64 v[8:9], v[4:5], 0, v[10:11]
	global_load_dword v36, v[8:9], off
	global_load_dword v26, v[8:9], off offset:256
	global_load_dword v37, v[8:9], off offset:512
	global_load_dword v27, v[8:9], off offset:768
	global_load_dword v38, v[8:9], off offset:1024
	global_load_dword v28, v[8:9], off offset:1280
	global_load_dword v39, v[8:9], off offset:1536
	s_nop 0
	global_load_dword v29, v[8:9], off offset:1792
	v_mov_b32_e32 v9, v129
	v_or_b32_e32 v8, 0x3000, v6
	v_lshl_add_u64 v[6:7], v[4:5], 0, v[8:9]
	global_load_dword v40, v[6:7], off
	global_load_dword v30, v[6:7], off offset:256
	global_load_dword v41, v[6:7], off offset:512
	global_load_dword v31, v[6:7], off offset:768
	global_load_dword v42, v[6:7], off offset:1024
	global_load_dword v56, v[6:7], off offset:1280
	global_load_dword v43, v[6:7], off offset:1536
	s_nop 0
	global_load_dword v57, v[6:7], off offset:1792
	v_lshl_add_u64 v[16:17], v[4:5], 0, s[66:67]
	global_load_dword v58, v[12:13], off offset:128
	global_load_dword v62, v[12:13], off offset:384
	v_lshl_add_u64 v[10:11], v[16:17], 0, v[10:11]
	v_lshl_add_u64 v[8:9], v[16:17], 0, v[8:9]
	global_load_dword v59, v[12:13], off offset:640
	global_load_dword v63, v[12:13], off offset:896
	global_load_dword v60, v[12:13], off offset:1152
	global_load_dword v64, v[12:13], off offset:1408
	global_load_dword v61, v[12:13], off offset:1664
	s_nop 0
	global_load_dword v65, v[12:13], off offset:1920
	v_lshl_add_u64 v[12:13], v[16:17], 0, v[14:15]
	global_load_dword v44, v[12:13], off
	global_load_dword v74, v[12:13], off offset:256
	global_load_dword v45, v[12:13], off offset:512
	global_load_dword v75, v[12:13], off offset:768
	global_load_dword v46, v[12:13], off offset:1024
	global_load_dword v76, v[12:13], off offset:1280
	global_load_dword v47, v[12:13], off offset:1536
	s_nop 0
	global_load_dword v77, v[12:13], off offset:1792
	global_load_dword v48, v[10:11], off
	global_load_dword v78, v[10:11], off offset:256
	global_load_dword v49, v[10:11], off offset:512
	global_load_dword v79, v[10:11], off offset:768
	global_load_dword v50, v[10:11], off offset:1024
	global_load_dword v80, v[10:11], off offset:1280
	global_load_dword v51, v[10:11], off offset:1536
	s_nop 0
	global_load_dword v81, v[10:11], off offset:1792
	global_load_dword v52, v[8:9], off
	global_load_dword v82, v[8:9], off offset:256
	global_load_dword v53, v[8:9], off offset:512
	global_load_dword v83, v[8:9], off offset:768
	global_load_dword v54, v[8:9], off offset:1024
	global_load_dword v84, v[8:9], off offset:1280
	s_waitcnt vmcnt(30)
	v_cvt_pk_bf16_f32 v0, v0, v18
	v_cvt_pk_bf16_f32 v1, v1, v19
	v_cvt_pk_bf16_f32 v2, v2, v20
	v_cvt_pk_bf16_f32 v3, v3, v21
	v_cvt_pk_bf16_f32 v32, v32, v22
	v_cvt_pk_bf16_f32 v33, v33, v23
	v_cvt_pk_bf16_f32 v34, v34, v24
	v_cvt_pk_bf16_f32 v35, v35, v25
	v_cvt_pk_bf16_f32 v36, v36, v26
	v_cvt_pk_bf16_f32 v37, v37, v27
	v_cvt_pk_bf16_f32 v38, v38, v28
	v_cvt_pk_bf16_f32 v39, v39, v29
	v_cvt_pk_bf16_f32 v40, v40, v30
	v_cvt_pk_bf16_f32 v41, v41, v31
	v_cvt_pk_bf16_f32 v42, v42, v56
	v_cvt_pk_bf16_f32 v43, v43, v57
	global_load_dword v55, v[8:9], off offset:1536
	s_nop 0
	global_load_dword v85, v[8:9], off offset:1792
	s_waitcnt vmcnt(0)
; DI unsigned pk2(float lo, float hi) { const f32x2 v = {lo, hi}; return __builtin_bit_cast(unsigned, __builtin_convertvector(v, bf16x2_t)); }
; DI void mixer_tile(unsigned char* smem_, const Params& p, int layer, const bf16_t* __restrict__ proj, bf16_t* __restrict__ y, int tile_) {
;     ...
;                 u32x4 w; w.x = pk2(wp[0], wp[64]); w.y = pk2(wp[128], wp[192]); w.z = pk2(wp[256], wp[320]); w.w = pk2(wp[384], wp[448]);
;                 wf[eh][kk] = __builtin_bit_cast(bf16x8, w);
;             }
;         float pv[47];
; #pragma unroll
;         for (int r = 0; r < 47; ++r) pv[r] = U[r * 256 + tid];
; #pragma unroll
;         for (int t = 0; t < 32; ++t) {
;             float s = 0.f;
; #pragma unroll
;             for (int j = 0; j < 16; ++j) s += (j < win) ? pv[t + 15 - j] : 0.f;
;             const int cnt = min(pos0 + t + 1, win);
;             U[t * 256 + tid] = s * __builtin_amdgcn_rcpf((float)cnt) - pv[t + 15];
;         }
	v_cvt_pk_bf16_f32 v4, v58, v62
	v_cvt_pk_bf16_f32 v5, v59, v63
	v_cvt_pk_bf16_f32 v6, v60, v64
	v_cvt_pk_bf16_f32 v7, v61, v65
	v_cvt_pk_bf16_f32 v44, v44, v74
	v_cvt_pk_bf16_f32 v45, v45, v75
	v_cvt_pk_bf16_f32 v46, v46, v76
	v_cvt_pk_bf16_f32 v47, v47, v77
	v_cvt_pk_bf16_f32 v48, v48, v78
	v_cvt_pk_bf16_f32 v49, v49, v79
	v_cvt_pk_bf16_f32 v50, v50, v80
	v_cvt_pk_bf16_f32 v51, v51, v81
	v_cvt_pk_bf16_f32 v52, v52, v82
	v_cvt_pk_bf16_f32 v53, v53, v83
	v_cvt_pk_bf16_f32 v54, v54, v84
	v_cvt_pk_bf16_f32 v55, v55, v85
	ds_read2st64_b32 v[74:75], v72 offset1:4
	ds_read2st64_b32 v[76:77], v72 offset0:8 offset1:12
	ds_read2st64_b32 v[78:79], v72 offset0:16 offset1:20
	ds_read2st64_b32 v[80:81], v72 offset0:24 offset1:28
	ds_read2st64_b32 v[82:83], v72 offset0:32 offset1:36
	ds_read2st64_b32 v[84:85], v72 offset0:40 offset1:44
	ds_read2st64_b32 v[64:65], v72 offset0:48 offset1:52
	ds_read2st64_b32 v[62:63], v72 offset0:56 offset1:60
	ds_read2st64_b32 v[60:61], v72 offset0:64 offset1:68
	ds_read2st64_b32 v[58:59], v72 offset0:72 offset1:76
	ds_read2st64_b32 v[56:57], v72 offset0:80 offset1:84
	ds_read2st64_b32 v[30:31], v72 offset0:88 offset1:92
	ds_read2st64_b32 v[28:29], v72 offset0:96 offset1:100
	ds_read2st64_b32 v[26:27], v72 offset0:104 offset1:108
	ds_read2st64_b32 v[24:25], v72 offset0:112 offset1:116
	ds_read2st64_b32 v[22:23], v72 offset0:120 offset1:124
	ds_read2st64_b32 v[20:21], v72 offset0:128 offset1:132
	ds_read2st64_b32 v[18:19], v72 offset0:136 offset1:140
	ds_read2st64_b32 v[14:15], v72 offset0:144 offset1:148
	ds_read2st64_b32 v[8:9], v72 offset0:152 offset1:156
	ds_read2st64_b32 v[16:17], v72 offset0:160 offset1:164
	ds_read2st64_b32 v[10:11], v72 offset0:168 offset1:172
	ds_read2st64_b32 v[12:13], v72 offset0:176 offset1:180
	ds_read_b32 v70, v72 offset:47104
	s_waitcnt lgkmcnt(14)
	v_add_f32_e32 v86, 0, v63
	v_add_f32_e32 v86, v62, v86
	v_cndmask_b32_e64 v87, v65, 0, s[0:1]
	v_add_f32_e32 v86, v87, v86
	v_cndmask_b32_e64 v90, v64, 0, s[0:1]
	v_add_f32_e32 v86, v90, v86
	v_cndmask_b32_e32 v90, 0, v85, vcc
	v_add_f32_e32 v86, v90, v86
	v_cndmask_b32_e32 v91, 0, v84, vcc
	v_add_f32_e32 v86, v91, v86
	v_cndmask_b32_e32 v93, 0, v83, vcc
	v_add_f32_e32 v86, v93, v86
	v_cndmask_b32_e32 v94, 0, v82, vcc
	v_add_f32_e32 v86, v94, v86
	v_cndmask_b32_e64 v73, 0, v81, s[2:3]
	v_add_f32_e32 v81, v73, v86
	v_cndmask_b32_e64 v80, 0, v80, s[2:3]
	v_add_f32_e32 v81, v80, v81
	v_cndmask_b32_e64 v79, 0, v79, s[2:3]
	v_add_f32_e32 v81, v79, v81
	v_cndmask_b32_e64 v78, 0, v78, s[2:3]
	v_add_f32_e32 v81, v78, v81
	v_cndmask_b32_e64 v77, 0, v77, s[2:3]
	v_add_f32_e32 v81, v77, v81
	v_cndmask_b32_e64 v76, 0, v76, s[2:3]
	v_add_f32_e32 v81, v76, v81
	v_cndmask_b32_e64 v75, 0, v75, s[2:3]
	v_add_f32_e32 v81, v75, v81
	v_cndmask_b32_e64 v74, 0, v74, s[2:3]
	v_add_f32_e32 v74, v74, v81
	v_min_u32_e32 v81, s20, v71
	v_cvt_f32_ubyte0_e32 v81, v81
	v_rcp_iflag_f32_e32 v81, v81
	v_cndmask_b32_e64 v86, v62, 0, s[0:1]
	v_cndmask_b32_e64 v82, 0, v82, s[2:3]
	s_or_b32 s20, s18, 2
	v_fma_f32 v74, v81, v74, -v63
	v_add_f32_e32 v81, 0, v60
	v_add_f32_e32 v81, v63, v81
	v_add_f32_e32 v81, v86, v81
	v_add_f32_e32 v81, v87, v81
	v_cndmask_b32_e32 v87, 0, v64, vcc
	v_add_f32_e32 v81, v87, v81
	v_add_f32_e32 v81, v90, v81
	v_add_f32_e32 v81, v91, v81
	v_add_f32_e32 v81, v93, v81
	v_add_f32_e32 v81, v82, v81
	v_add_f32_e32 v81, v73, v81
	v_add_f32_e32 v81, v80, v81
	v_add_f32_e32 v81, v79, v81
	v_add_f32_e32 v81, v78, v81
	v_add_f32_e32 v81, v77, v81
	v_add_f32_e32 v81, v76, v81
	v_add_f32_e32 v75, v75, v81
	v_min_u32_e32 v81, s20, v71
	v_cvt_f32_ubyte0_e32 v81, v81
	v_rcp_iflag_f32_e32 v81, v81
	v_cndmask_b32_e64 v83, 0, v83, s[2:3]
	s_or_b32 s20, s18, 3
	v_cndmask_b32_e64 v84, 0, v84, s[2:3]
	v_fma_f32 v75, v81, v75, -v60
	ds_write2st64_b32 v72, v74, v75 offset1:4
	v_add_f32_e32 v74, 0, v61
	v_add_f32_e32 v74, v60, v74
	v_cndmask_b32_e64 v75, v63, 0, s[0:1]
	v_add_f32_e32 v74, v75, v74
	v_add_f32_e32 v74, v86, v74
	v_cndmask_b32_e32 v81, 0, v65, vcc
	v_add_f32_e32 v74, v81, v74
	v_add_f32_e32 v74, v87, v74
	v_add_f32_e32 v74, v90, v74
	v_add_f32_e32 v74, v91, v74
	v_add_f32_e32 v74, v83, v74
	v_add_f32_e32 v74, v82, v74
	v_add_f32_e32 v74, v73, v74
	v_add_f32_e32 v74, v80, v74
	v_add_f32_e32 v74, v79, v74
	v_add_f32_e32 v74, v78, v74
	v_add_f32_e32 v74, v77, v74
	v_add_f32_e32 v74, v76, v74
	v_min_u32_e32 v76, s20, v71
	v_cvt_f32_ubyte0_e32 v76, v76
	v_rcp_iflag_f32_e32 v76, v76
	v_cndmask_b32_e64 v86, v60, 0, s[0:1]
	s_or_b32 s20, s18, 4
	v_cndmask_b32_e64 v85, 0, v85, s[2:3]
	v_fma_f32 v74, v76, v74, -v61
	v_add_f32_e32 v76, 0, v58
	v_add_f32_e32 v76, v61, v76
	v_add_f32_e32 v76, v86, v76
	v_add_f32_e32 v75, v75, v76
	v_cndmask_b32_e32 v76, 0, v62, vcc
	v_add_f32_e32 v75, v76, v75
	v_add_f32_e32 v75, v81, v75
	v_add_f32_e32 v75, v87, v75
	v_add_f32_e32 v75, v90, v75
	v_add_f32_e32 v75, v84, v75
	v_add_f32_e32 v75, v83, v75
	v_add_f32_e32 v75, v82, v75
	v_add_f32_e32 v75, v73, v75
	v_add_f32_e32 v75, v80, v75
	v_add_f32_e32 v75, v79, v75
	v_add_f32_e32 v75, v78, v75
	v_add_f32_e32 v75, v77, v75
	v_min_u32_e32 v77, s20, v71
	v_cvt_f32_ubyte0_e32 v77, v77
	v_rcp_iflag_f32_e32 v77, v77
	s_or_b32 s20, s18, 5
	v_cndmask_b32_e64 v64, 0, v64, s[2:3]
	v_cndmask_b32_e64 v65, 0, v65, s[2:3]
	v_fma_f32 v75, v77, v75, -v58
	ds_write2st64_b32 v72, v74, v75 offset0:8 offset1:12
	v_add_f32_e32 v74, 0, v59
	v_add_f32_e32 v74, v58, v74
	v_cndmask_b32_e64 v75, v61, 0, s[0:1]
	v_add_f32_e32 v74, v75, v74
	v_add_f32_e32 v74, v86, v74
	v_cndmask_b32_e32 v77, 0, v63, vcc
	v_add_f32_e32 v74, v77, v74
	v_add_f32_e32 v74, v76, v74
	v_add_f32_e32 v74, v81, v74
	v_add_f32_e32 v74, v87, v74
	v_add_f32_e32 v74, v85, v74
	v_add_f32_e32 v74, v84, v74
	v_add_f32_e32 v74, v83, v74
	v_add_f32_e32 v74, v82, v74
	v_add_f32_e32 v74, v73, v74
	v_add_f32_e32 v74, v80, v74
	v_add_f32_e32 v74, v79, v74
	v_add_f32_e32 v74, v78, v74
	v_min_u32_e32 v78, s20, v71
	v_cvt_f32_ubyte0_e32 v78, v78
	v_rcp_iflag_f32_e32 v78, v78
	v_cndmask_b32_e64 v86, v58, 0, s[0:1]
	s_or_b32 s20, s18, 6
	v_cndmask_b32_e64 v62, 0, v62, s[2:3]
	v_fma_f32 v74, v78, v74, -v59
	s_waitcnt lgkmcnt(14)
; DI void mixer_tile(unsigned char* smem_, const Params& p, int layer, const bf16_t* __restrict__ proj, bf16_t* __restrict__ y, int tile_) {
;     ...
;         float pv[47];
; #pragma unroll
;         for (int r = 0; r < 47; ++r) pv[r] = U[r * 256 + tid];
; #pragma unroll
;         for (int t = 0; t < 32; ++t) {
;             float s = 0.f;
; #pragma unroll
;             for (int j = 0; j < 16; ++j) s += (j < win) ? pv[t + 15 - j] : 0.f;
;             const int cnt = min(pos0 + t + 1, win);
;             U[t * 256 + tid] = s * __builtin_amdgcn_rcpf((float)cnt) - pv[t + 15];
;         }
	v_add_f32_e32 v78, 0, v56
	v_add_f32_e32 v78, v59, v78
	v_add_f32_e32 v78, v86, v78
	v_add_f32_e32 v75, v75, v78
	v_cndmask_b32_e32 v78, 0, v60, vcc
	v_add_f32_e32 v75, v78, v75
	v_add_f32_e32 v75, v77, v75
	v_add_f32_e32 v75, v76, v75
	v_add_f32_e32 v75, v81, v75
	v_add_f32_e32 v75, v64, v75
	v_add_f32_e32 v75, v85, v75
	v_add_f32_e32 v75, v84, v75
	v_add_f32_e32 v75, v83, v75
	v_add_f32_e32 v75, v82, v75
	v_add_f32_e32 v75, v73, v75
	v_add_f32_e32 v75, v80, v75
	v_add_f32_e32 v75, v79, v75
	v_min_u32_e32 v79, s20, v71
	v_cvt_f32_ubyte0_e32 v79, v79
	v_rcp_iflag_f32_e32 v79, v79
	s_or_b32 s20, s18, 7
	v_cndmask_b32_e64 v63, 0, v63, s[2:3]
	v_cndmask_b32_e64 v60, 0, v60, s[2:3]
	v_fma_f32 v75, v79, v75, -v56
	ds_write2st64_b32 v72, v74, v75 offset0:16 offset1:20
	v_add_f32_e32 v74, 0, v57
	v_add_f32_e32 v74, v56, v74
	v_cndmask_b32_e64 v75, v59, 0, s[0:1]
	v_add_f32_e32 v74, v75, v74
	v_add_f32_e32 v74, v86, v74
	v_cndmask_b32_e32 v79, 0, v61, vcc
	v_add_f32_e32 v74, v79, v74
	v_add_f32_e32 v74, v78, v74
	v_add_f32_e32 v74, v77, v74
	v_add_f32_e32 v74, v76, v74
	v_add_f32_e32 v74, v65, v74
	v_add_f32_e32 v74, v64, v74
	v_add_f32_e32 v74, v85, v74
	v_min_u32_e32 v76, s20, v71
	v_add_f32_e32 v74, v84, v74
	v_cvt_f32_ubyte0_e32 v76, v76
	v_add_f32_e32 v74, v83, v74
	v_rcp_iflag_f32_e32 v76, v76
	v_add_f32_e32 v74, v82, v74
	v_add_f32_e32 v74, v73, v74
	v_add_f32_e32 v74, v80, v74
	v_fma_f32 v74, v76, v74, -v57
	v_add_f32_e32 v76, 0, v30
	v_add_f32_e32 v76, v57, v76
	v_cndmask_b32_e64 v80, v56, 0, s[0:1]
	v_add_f32_e32 v76, v80, v76
	v_add_f32_e32 v75, v75, v76
	v_cndmask_b32_e32 v76, 0, v58, vcc
	v_add_f32_e32 v75, v76, v75
	v_add_f32_e32 v75, v79, v75
	v_add_f32_e32 v75, v78, v75
	v_add_f32_e32 v75, v77, v75
	v_add_f32_e32 v75, v62, v75
	v_add_f32_e32 v75, v65, v75
	v_add_f32_e32 v75, v64, v75
	v_add_f32_e32 v75, v85, v75
	v_add_f32_e32 v75, v84, v75
	v_add_f32_e32 v75, v83, v75
	v_add_f32_e32 v75, v82, v75
	s_or_b32 s20, s18, 8
	v_add_f32_e32 v73, v73, v75
	v_min_u32_e32 v75, s20, v71
	v_cvt_f32_ubyte0_e32 v75, v75
	v_rcp_iflag_f32_e32 v75, v75
	s_or_b32 s20, s18, 9
	v_min_u32_e32 v77, s20, v71
	v_cvt_f32_ubyte0_e32 v77, v77
	v_fma_f32 v73, v75, v73, -v30
	ds_write2st64_b32 v72, v74, v73 offset0:24 offset1:28
	v_add_f32_e32 v73, 0, v31
	v_add_f32_e32 v73, v30, v73
	v_cndmask_b32_e64 v74, v57, 0, s[0:1]
	v_add_f32_e32 v73, v74, v73
	v_add_f32_e32 v73, v80, v73
	v_cndmask_b32_e32 v75, 0, v59, vcc
	v_add_f32_e32 v73, v75, v73
	v_add_f32_e32 v73, v76, v73
	v_add_f32_e32 v73, v79, v73
	v_add_f32_e32 v73, v78, v73
	v_add_f32_e32 v73, v63, v73
	v_add_f32_e32 v73, v62, v73
	v_add_f32_e32 v73, v65, v73
	v_add_f32_e32 v73, v64, v73
	v_add_f32_e32 v73, v85, v73
	v_rcp_iflag_f32_e32 v77, v77
	v_add_f32_e32 v73, v84, v73
	v_add_f32_e32 v73, v83, v73
	v_add_f32_e32 v73, v82, v73
	v_fma_f32 v73, v77, v73, -v31
	s_waitcnt lgkmcnt(14)
	v_add_f32_e32 v77, 0, v28
	v_add_f32_e32 v77, v31, v77
	v_cndmask_b32_e64 v78, v30, 0, s[0:1]
	v_add_f32_e32 v77, v78, v77
	v_add_f32_e32 v74, v74, v77
	v_cndmask_b32_e32 v77, 0, v56, vcc
	v_add_f32_e32 v74, v77, v74
	v_add_f32_e32 v74, v75, v74
	v_add_f32_e32 v74, v76, v74
	v_add_f32_e32 v74, v79, v74
	v_add_f32_e32 v74, v60, v74
	v_add_f32_e32 v74, v63, v74
	s_or_b32 s20, s18, 10
	v_add_f32_e32 v74, v62, v74
	v_min_u32_e32 v79, s20, v71
	v_add_f32_e32 v74, v65, v74
	v_cvt_f32_ubyte0_e32 v79, v79
	v_add_f32_e32 v74, v64, v74
	v_rcp_iflag_f32_e32 v79, v79
	v_add_f32_e32 v74, v85, v74
	v_add_f32_e32 v74, v84, v74
	v_add_f32_e32 v74, v83, v74
	v_fma_f32 v74, v79, v74, -v28
	ds_write2st64_b32 v72, v73, v74 offset0:32 offset1:36
	v_add_f32_e32 v73, 0, v29
	v_add_f32_e32 v73, v28, v73
	v_cndmask_b32_e64 v74, v31, 0, s[0:1]
	v_add_f32_e32 v73, v74, v73
	v_add_f32_e32 v73, v78, v73
	v_cndmask_b32_e32 v78, 0, v57, vcc
	v_add_f32_e32 v73, v78, v73
	v_add_f32_e32 v73, v77, v73
	v_add_f32_e32 v73, v75, v73
	v_add_f32_e32 v73, v76, v73
	v_cndmask_b32_e64 v61, 0, v61, s[2:3]
	v_add_f32_e32 v73, v61, v73
	v_add_f32_e32 v73, v60, v73
	s_or_b32 s20, s18, 11
	v_add_f32_e32 v73, v63, v73
	v_min_u32_e32 v76, s20, v71
	v_add_f32_e32 v73, v62, v73
	v_cvt_f32_ubyte0_e32 v76, v76
	v_add_f32_e32 v73, v65, v73
	v_rcp_iflag_f32_e32 v76, v76
	v_add_f32_e32 v73, v64, v73
	v_add_f32_e32 v73, v85, v73
	v_add_f32_e32 v73, v84, v73
	v_fma_f32 v73, v76, v73, -v29
	v_add_f32_e32 v76, 0, v26
	v_add_f32_e32 v76, v29, v76
	v_cndmask_b32_e64 v79, v28, 0, s[0:1]
	v_add_f32_e32 v76, v79, v76
	v_add_f32_e32 v74, v74, v76
	v_cndmask_b32_e32 v76, 0, v30, vcc
	v_add_f32_e32 v74, v76, v74
	v_add_f32_e32 v74, v78, v74
	v_add_f32_e32 v74, v77, v74
	v_add_f32_e32 v74, v75, v74
	v_cndmask_b32_e64 v58, 0, v58, s[2:3]
	v_add_f32_e32 v74, v58, v74
	v_add_f32_e32 v74, v61, v74
	s_or_b32 s20, s18, 12
	v_add_f32_e32 v74, v60, v74
	v_min_u32_e32 v75, s20, v71
	v_add_f32_e32 v74, v63, v74
	v_cvt_f32_ubyte0_e32 v75, v75
	v_add_f32_e32 v74, v62, v74
	v_rcp_iflag_f32_e32 v75, v75
	v_add_f32_e32 v74, v65, v74
	v_add_f32_e32 v74, v64, v74
	v_add_f32_e32 v74, v85, v74
	v_fma_f32 v74, v75, v74, -v26
	ds_write2st64_b32 v72, v73, v74 offset0:40 offset1:44
	v_add_f32_e32 v73, 0, v27
	v_add_f32_e32 v73, v26, v73
	v_cndmask_b32_e64 v74, v29, 0, s[0:1]
	v_add_f32_e32 v73, v74, v73
	v_add_f32_e32 v73, v79, v73
	v_cndmask_b32_e32 v75, 0, v31, vcc
	v_add_f32_e32 v73, v75, v73
	v_add_f32_e32 v73, v76, v73
	v_add_f32_e32 v73, v78, v73
	v_add_f32_e32 v73, v77, v73
	v_cndmask_b32_e64 v59, 0, v59, s[2:3]
	v_add_f32_e32 v73, v59, v73
	v_add_f32_e32 v73, v58, v73
	v_add_f32_e32 v73, v61, v73
	v_add_f32_e32 v73, v60, v73
	v_add_f32_e32 v73, v63, v73
	v_add_f32_e32 v73, v62, v73
	v_add_f32_e32 v73, v65, v73
	s_or_b32 s20, s18, 13
	v_add_f32_e32 v64, v64, v73
	v_min_u32_e32 v73, s20, v71
	v_cvt_f32_ubyte0_e32 v73, v73
	v_rcp_iflag_f32_e32 v73, v73
	v_cndmask_b32_e64 v77, v26, 0, s[0:1]
	v_cndmask_b32_e64 v56, 0, v56, s[2:3]
	s_or_b32 s20, s18, 14
	v_fma_f32 v64, v73, v64, -v27
	s_waitcnt lgkmcnt(14)
; DI void mixer_tile(unsigned char* smem_, const Params& p, int layer, const bf16_t* __restrict__ proj, bf16_t* __restrict__ y, int tile_) {
;     ...
;         float pv[47];
; #pragma unroll
;         for (int r = 0; r < 47; ++r) pv[r] = U[r * 256 + tid];
; #pragma unroll
;         for (int t = 0; t < 32; ++t) {
;             float s = 0.f;
; #pragma unroll
;             for (int j = 0; j < 16; ++j) s += (j < win) ? pv[t + 15 - j] : 0.f;
;             const int cnt = min(pos0 + t + 1, win);
;             U[t * 256 + tid] = s * __builtin_amdgcn_rcpf((float)cnt) - pv[t + 15];
;         }
	v_add_f32_e32 v73, 0, v24
	v_add_f32_e32 v73, v27, v73
	v_add_f32_e32 v73, v77, v73
	v_add_f32_e32 v73, v74, v73
	v_cndmask_b32_e32 v74, 0, v28, vcc
	v_add_f32_e32 v73, v74, v73
	v_add_f32_e32 v73, v75, v73
	v_add_f32_e32 v73, v76, v73
	v_add_f32_e32 v73, v78, v73
	v_add_f32_e32 v73, v56, v73
	v_add_f32_e32 v73, v59, v73
	v_add_f32_e32 v73, v58, v73
	v_add_f32_e32 v73, v61, v73
	v_add_f32_e32 v73, v60, v73
	v_add_f32_e32 v73, v63, v73
	v_add_f32_e32 v73, v62, v73
	v_add_f32_e32 v65, v65, v73
	v_min_u32_e32 v73, s20, v71
	v_cvt_f32_ubyte0_e32 v73, v73
	v_rcp_iflag_f32_e32 v73, v73
	v_cndmask_b32_e64 v57, 0, v57, s[2:3]
	s_or_b32 s20, s18, 15
	v_cndmask_b32_e64 v30, 0, v30, s[2:3]
	v_fma_f32 v65, v73, v65, -v24
	ds_write2st64_b32 v72, v64, v65 offset0:48 offset1:52
	v_add_f32_e32 v64, 0, v25
	v_add_f32_e32 v64, v24, v64
	v_cndmask_b32_e64 v65, v27, 0, s[0:1]
	v_add_f32_e32 v64, v65, v64
	v_add_f32_e32 v64, v77, v64
	v_cndmask_b32_e32 v73, 0, v29, vcc
	v_add_f32_e32 v64, v73, v64
	v_add_f32_e32 v64, v74, v64
	v_add_f32_e32 v64, v75, v64
	v_add_f32_e32 v64, v76, v64
	v_add_f32_e32 v64, v57, v64
	v_add_f32_e32 v64, v56, v64
	v_add_f32_e32 v64, v59, v64
	v_add_f32_e32 v64, v58, v64
	v_add_f32_e32 v64, v61, v64
	v_add_f32_e32 v64, v60, v64
	v_add_f32_e32 v64, v63, v64
	v_add_f32_e32 v62, v62, v64
	v_min_u32_e32 v64, s20, v71
	v_cvt_f32_ubyte0_e32 v64, v64
	v_rcp_iflag_f32_e32 v64, v64
	v_cndmask_b32_e64 v76, v24, 0, s[0:1]
	v_cndmask_b32_e64 v31, 0, v31, s[2:3]
	v_cndmask_b32_e64 v28, 0, v28, s[2:3]
	v_fma_f32 v62, v64, v62, -v25
	v_add_f32_e32 v64, 0, v22
	v_add_f32_e32 v64, v25, v64
	v_add_f32_e32 v64, v76, v64
	v_add_f32_e32 v64, v65, v64
	v_cndmask_b32_e32 v65, 0, v26, vcc
	v_add_f32_e32 v64, v65, v64
	v_add_f32_e32 v64, v73, v64
	v_add_f32_e32 v64, v74, v64
	v_add_f32_e32 v64, v75, v64
	v_add_f32_e32 v64, v30, v64
	v_add_f32_e32 v64, v57, v64
	v_add_f32_e32 v64, v56, v64
	v_add_f32_e32 v64, v59, v64
	v_add_f32_e32 v64, v58, v64
	v_add_f32_e32 v64, v61, v64
	v_add_f32_e32 v64, v60, v64
	v_add_f32_e32 v63, v63, v64
	v_cvt_f32_ubyte0_e32 v64, v71
	v_rcp_iflag_f32_e32 v64, v64
	v_cndmask_b32_e32 v71, 0, v27, vcc
	v_cndmask_b32_e64 v29, 0, v29, s[2:3]
	v_cndmask_b32_e64 v26, 0, v26, s[2:3]
	v_fma_f32 v63, v64, v63, -v22
	ds_write2st64_b32 v72, v62, v63 offset0:56 offset1:60
	v_add_f32_e32 v62, 0, v23
	v_add_f32_e32 v62, v22, v62
	v_cndmask_b32_e64 v63, v25, 0, s[0:1]
	v_add_f32_e32 v62, v63, v62
	v_add_f32_e32 v62, v76, v62
	v_add_f32_e32 v62, v71, v62
	v_add_f32_e32 v62, v65, v62
	v_add_f32_e32 v62, v73, v62
	v_add_f32_e32 v62, v74, v62
	v_add_f32_e32 v62, v31, v62
	v_add_f32_e32 v62, v30, v62
	v_add_f32_e32 v62, v57, v62
	v_add_f32_e32 v62, v56, v62
	v_add_f32_e32 v62, v59, v62
	v_add_f32_e32 v62, v58, v62
	v_add_f32_e32 v62, v61, v62
	v_add_f32_e32 v60, v60, v62
	s_waitcnt lgkmcnt(14)
	v_add_f32_e32 v62, 0, v20
	v_add_f32_e32 v62, v23, v62
	v_cndmask_b32_e64 v74, v22, 0, s[0:1]
	v_add_f32_e32 v62, v74, v62
	v_add_f32_e32 v62, v63, v62
	v_cndmask_b32_e32 v63, 0, v24, vcc
	v_add_f32_e32 v62, v63, v62
	v_add_f32_e32 v62, v71, v62
	v_add_f32_e32 v62, v65, v62
	v_add_f32_e32 v62, v73, v62
	v_add_f32_e32 v62, v28, v62
	v_add_f32_e32 v62, v31, v62
	v_add_f32_e32 v62, v30, v62
	v_add_f32_e32 v62, v57, v62
	v_add_f32_e32 v62, v56, v62
	v_add_f32_e32 v62, v59, v62
	v_add_f32_e32 v62, v58, v62
	v_add_f32_e32 v61, v61, v62
	v_fma_f32 v60, v64, v60, -v23
	v_fma_f32 v61, v64, v61, -v20
	ds_write2st64_b32 v72, v60, v61 offset0:64 offset1:68
	v_add_f32_e32 v60, 0, v21
	v_add_f32_e32 v60, v20, v60
	v_cndmask_b32_e64 v61, v23, 0, s[0:1]
	v_add_f32_e32 v60, v61, v60
	v_add_f32_e32 v60, v74, v60
	v_cndmask_b32_e32 v62, 0, v25, vcc
	v_add_f32_e32 v60, v62, v60
	v_add_f32_e32 v60, v63, v60
	v_add_f32_e32 v60, v71, v60
	v_add_f32_e32 v60, v65, v60
	v_add_f32_e32 v60, v29, v60
	v_add_f32_e32 v60, v28, v60
	v_add_f32_e32 v60, v31, v60
	v_add_f32_e32 v60, v30, v60
	v_add_f32_e32 v60, v57, v60
	v_add_f32_e32 v60, v56, v60
	v_add_f32_e32 v60, v59, v60
	v_add_f32_e32 v58, v58, v60
	v_add_f32_e32 v60, 0, v18
	v_add_f32_e32 v60, v21, v60
	v_cndmask_b32_e64 v65, v20, 0, s[0:1]
	v_add_f32_e32 v60, v65, v60
	v_add_f32_e32 v60, v61, v60
	v_cndmask_b32_e32 v61, 0, v22, vcc
	v_add_f32_e32 v60, v61, v60
	v_add_f32_e32 v60, v62, v60
	v_add_f32_e32 v60, v63, v60
	v_add_f32_e32 v60, v71, v60
	v_add_f32_e32 v60, v26, v60
	v_add_f32_e32 v60, v29, v60
	v_add_f32_e32 v60, v28, v60
	v_add_f32_e32 v60, v31, v60
	v_add_f32_e32 v60, v30, v60
	v_add_f32_e32 v60, v57, v60
	v_add_f32_e32 v60, v56, v60
	v_add_f32_e32 v59, v59, v60
	v_fma_f32 v58, v64, v58, -v21
	v_fma_f32 v59, v64, v59, -v18
	ds_write2st64_b32 v72, v58, v59 offset0:72 offset1:76
	v_add_f32_e32 v58, 0, v19
	v_add_f32_e32 v58, v18, v58
	v_cndmask_b32_e64 v59, v21, 0, s[0:1]
	v_add_f32_e32 v58, v59, v58
	v_add_f32_e32 v58, v65, v58
	v_cndmask_b32_e32 v60, 0, v23, vcc
	v_add_f32_e32 v58, v60, v58
	v_add_f32_e32 v58, v61, v58
	v_add_f32_e32 v58, v62, v58
	v_add_f32_e32 v58, v63, v58
	v_cndmask_b32_e64 v27, 0, v27, s[2:3]
	v_add_f32_e32 v58, v27, v58
	v_add_f32_e32 v58, v26, v58
	v_add_f32_e32 v58, v29, v58
	v_add_f32_e32 v58, v28, v58
	v_add_f32_e32 v58, v31, v58
	v_add_f32_e32 v58, v30, v58
	v_add_f32_e32 v58, v57, v58
	v_add_f32_e32 v56, v56, v58
	s_waitcnt lgkmcnt(14)
; DI void mixer_tile(unsigned char* smem_, const Params& p, int layer, const bf16_t* __restrict__ proj, bf16_t* __restrict__ y, int tile_) {
;     ...
;         float pv[47];
; #pragma unroll
;         for (int r = 0; r < 47; ++r) pv[r] = U[r * 256 + tid];
; #pragma unroll
;         for (int t = 0; t < 32; ++t) {
;             float s = 0.f;
; #pragma unroll
;             for (int j = 0; j < 16; ++j) s += (j < win) ? pv[t + 15 - j] : 0.f;
;             const int cnt = min(pos0 + t + 1, win);
;             U[t * 256 + tid] = s * __builtin_amdgcn_rcpf((float)cnt) - pv[t + 15];
;         }
	v_add_f32_e32 v58, 0, v14
	v_add_f32_e32 v58, v19, v58
	v_cndmask_b32_e64 v63, v18, 0, s[0:1]
	v_add_f32_e32 v58, v63, v58
	v_add_f32_e32 v58, v59, v58
	v_cndmask_b32_e32 v59, 0, v20, vcc
	v_add_f32_e32 v58, v59, v58
	v_add_f32_e32 v58, v60, v58
	v_add_f32_e32 v58, v61, v58
	v_add_f32_e32 v58, v62, v58
	v_cndmask_b32_e64 v24, 0, v24, s[2:3]
	v_add_f32_e32 v58, v24, v58
	v_add_f32_e32 v58, v27, v58
	v_add_f32_e32 v58, v26, v58
	v_add_f32_e32 v58, v29, v58
	v_add_f32_e32 v58, v28, v58
	v_add_f32_e32 v58, v31, v58
	v_add_f32_e32 v58, v30, v58
	v_add_f32_e32 v57, v57, v58
	v_fma_f32 v56, v64, v56, -v19
	v_fma_f32 v57, v64, v57, -v14
	ds_write2st64_b32 v72, v56, v57 offset0:80 offset1:84
	v_add_f32_e32 v56, 0, v15
	v_add_f32_e32 v56, v14, v56
	v_cndmask_b32_e64 v57, v19, 0, s[0:1]
	v_add_f32_e32 v56, v57, v56
	v_add_f32_e32 v56, v63, v56
	v_cndmask_b32_e32 v58, 0, v21, vcc
	v_add_f32_e32 v56, v58, v56
	v_add_f32_e32 v56, v59, v56
	v_add_f32_e32 v56, v60, v56
	v_add_f32_e32 v56, v61, v56
	v_cndmask_b32_e64 v25, 0, v25, s[2:3]
	v_add_f32_e32 v56, v25, v56
	v_add_f32_e32 v56, v24, v56
	v_add_f32_e32 v56, v27, v56
	v_add_f32_e32 v56, v26, v56
	v_add_f32_e32 v56, v29, v56
	v_add_f32_e32 v56, v28, v56
	v_add_f32_e32 v56, v31, v56
	v_add_f32_e32 v30, v30, v56
	v_add_f32_e32 v56, 0, v8
	v_add_f32_e32 v56, v15, v56
	v_cndmask_b32_e64 v61, v14, 0, s[0:1]
	v_add_f32_e32 v56, v61, v56
	v_add_f32_e32 v56, v57, v56
	v_cndmask_b32_e32 v57, 0, v18, vcc
	v_add_f32_e32 v56, v57, v56
	v_add_f32_e32 v56, v58, v56
	v_add_f32_e32 v56, v59, v56
	v_add_f32_e32 v56, v60, v56
	v_cndmask_b32_e64 v22, 0, v22, s[2:3]
	v_add_f32_e32 v56, v22, v56
	v_add_f32_e32 v56, v25, v56
	v_add_f32_e32 v56, v24, v56
	v_add_f32_e32 v56, v27, v56
	v_add_f32_e32 v56, v26, v56
	v_add_f32_e32 v56, v29, v56
	v_add_f32_e32 v56, v28, v56
	v_add_f32_e32 v31, v31, v56
	v_fma_f32 v30, v64, v30, -v15
	v_fma_f32 v31, v64, v31, -v8
	ds_write2st64_b32 v72, v30, v31 offset0:88 offset1:92
	v_add_f32_e32 v30, 0, v9
	v_add_f32_e32 v30, v8, v30
	v_cndmask_b32_e64 v31, v15, 0, s[0:1]
	v_add_f32_e32 v30, v31, v30
	v_add_f32_e32 v30, v61, v30
	v_cndmask_b32_e32 v56, 0, v19, vcc
	v_add_f32_e32 v30, v56, v30
	v_add_f32_e32 v30, v57, v30
	v_add_f32_e32 v30, v58, v30
	v_add_f32_e32 v30, v59, v30
	v_cndmask_b32_e64 v23, 0, v23, s[2:3]
	v_add_f32_e32 v30, v23, v30
	v_add_f32_e32 v30, v22, v30
	v_add_f32_e32 v30, v25, v30
	v_add_f32_e32 v30, v24, v30
	v_add_f32_e32 v30, v27, v30
	v_add_f32_e32 v30, v26, v30
	v_add_f32_e32 v30, v29, v30
	v_add_f32_e32 v28, v28, v30
	s_waitcnt lgkmcnt(14)
	v_add_f32_e32 v30, 0, v16
	v_add_f32_e32 v30, v9, v30
	v_cndmask_b32_e64 v59, v8, 0, s[0:1]
	v_add_f32_e32 v30, v59, v30
	v_add_f32_e32 v30, v31, v30
	v_cndmask_b32_e32 v31, 0, v14, vcc
	v_add_f32_e32 v30, v31, v30
	v_add_f32_e32 v30, v56, v30
	v_add_f32_e32 v30, v57, v30
	v_add_f32_e32 v30, v58, v30
	v_cndmask_b32_e64 v20, 0, v20, s[2:3]
	v_add_f32_e32 v30, v20, v30
	v_add_f32_e32 v30, v23, v30
	v_add_f32_e32 v30, v22, v30
	v_add_f32_e32 v30, v25, v30
	v_add_f32_e32 v30, v24, v30
	v_add_f32_e32 v30, v27, v30
	v_add_f32_e32 v30, v26, v30
	v_add_f32_e32 v29, v29, v30
	v_fma_f32 v28, v64, v28, -v9
	v_fma_f32 v29, v64, v29, -v16
	ds_write2st64_b32 v72, v28, v29 offset0:96 offset1:100
	v_add_f32_e32 v28, 0, v17
	v_add_f32_e32 v28, v16, v28
	v_cndmask_b32_e64 v29, v9, 0, s[0:1]
	v_add_f32_e32 v28, v29, v28
	v_add_f32_e32 v28, v59, v28
	v_cndmask_b32_e32 v30, 0, v15, vcc
	v_add_f32_e32 v28, v30, v28
	v_add_f32_e32 v28, v31, v28
	v_add_f32_e32 v28, v56, v28
	v_add_f32_e32 v28, v57, v28
	v_cndmask_b32_e64 v21, 0, v21, s[2:3]
	v_add_f32_e32 v28, v21, v28
	v_add_f32_e32 v28, v20, v28
	v_add_f32_e32 v28, v23, v28
	v_add_f32_e32 v28, v22, v28
	v_add_f32_e32 v28, v25, v28
	v_add_f32_e32 v28, v24, v28
	v_add_f32_e32 v28, v27, v28
	v_add_f32_e32 v26, v26, v28
	v_add_f32_e32 v28, 0, v10
	v_add_f32_e32 v28, v17, v28
	v_cndmask_b32_e64 v57, v16, 0, s[0:1]
	v_add_f32_e32 v28, v57, v28
	v_add_f32_e32 v28, v29, v28
	v_cndmask_b32_e32 v29, 0, v8, vcc
	v_add_f32_e32 v28, v29, v28
	v_add_f32_e32 v28, v30, v28
	v_add_f32_e32 v28, v31, v28
	v_add_f32_e32 v28, v56, v28
	v_cndmask_b32_e64 v18, 0, v18, s[2:3]
	v_add_f32_e32 v28, v18, v28
	v_add_f32_e32 v28, v21, v28
	v_add_f32_e32 v28, v20, v28
	v_add_f32_e32 v28, v23, v28
	v_add_f32_e32 v28, v22, v28
	v_add_f32_e32 v28, v25, v28
	v_add_f32_e32 v28, v24, v28
	v_add_f32_e32 v27, v27, v28
	v_fma_f32 v26, v64, v26, -v17
	v_fma_f32 v27, v64, v27, -v10
	ds_write2st64_b32 v72, v26, v27 offset0:104 offset1:108
	v_add_f32_e32 v26, 0, v11
	v_add_f32_e32 v26, v10, v26
	v_cndmask_b32_e64 v27, v17, 0, s[0:1]
	v_add_f32_e32 v26, v27, v26
	v_add_f32_e32 v26, v57, v26
	v_cndmask_b32_e32 v9, 0, v9, vcc
	v_add_f32_e32 v26, v9, v26
	v_add_f32_e32 v26, v29, v26
	v_add_f32_e32 v26, v30, v26
	v_add_f32_e32 v26, v31, v26
	v_cndmask_b32_e64 v19, 0, v19, s[2:3]
	v_add_f32_e32 v26, v19, v26
	v_add_f32_e32 v26, v18, v26
	v_add_f32_e32 v26, v21, v26
	v_add_f32_e32 v26, v20, v26
	v_add_f32_e32 v26, v23, v26
	v_add_f32_e32 v26, v22, v26
	v_add_f32_e32 v26, v25, v26
	v_add_f32_e32 v24, v24, v26
	s_waitcnt lgkmcnt(14)
; #define MFMA32(a, b, c) __builtin_amdgcn_mfma_f32_32x32x16_bf16((a), (b), (c), 0, 0, 0)
; DI unsigned pk2(float lo, float hi) { const f32x2 v = {lo, hi}; return __builtin_bit_cast(unsigned, __builtin_convertvector(v, bf16x2_t)); }
; DI void mixer_tile(unsigned char* smem_, const Params& p, int layer, const bf16_t* __restrict__ proj, bf16_t* __restrict__ y, int tile_) {
;     ...
;             U[t * 256 + tid] = s * __builtin_amdgcn_rcpf((float)cnt) - pv[t + 15];
;         }
;         __syncthreads();
;         f32x16 acc[2];
; #pragma unroll
;         for (int i = 0; i < 16; ++i) { acc[0][i] = 0.f; acc[1][i] = 0.f; }
; #pragma unroll
;         for (int kk = 0; kk < 4; ++kk) {
;             const float* pp = U + l31 * 256 + g * 64 + 16 * kk + 8 * hi;
;             const f32x4 pa = *(const f32x4*)(pp), pb = *(const f32x4*)(pp + 4);
;             u32x4 pk; pk.x = pk2(pa.x, pa.y); pk.y = pk2(pa.z, pa.w); pk.z = pk2(pb.x, pb.y); pk.w = pk2(pb.z, pb.w);
;             const bf16x8 pf = __builtin_bit_cast(bf16x8, pk);
;             acc[0] = MFMA32(wf[0][kk], pf, acc[0]);
;             acc[1] = MFMA32(wf[1][kk], pf, acc[1]);
;         }
;         const float* scp = p.in[7] + layer * 256 + g * 64;
;         bf16_t* yr = y + (size_t)(tok0 + l31) * PA + 256 + g * 64 + 4 * hi;
; #pragma unroll
;         for (int eh = 0; eh < 2; ++eh)
; #pragma unroll
;             for (int gq = 0; gq < 4; ++gq) {
;                 const f32x4 sc = *(const f32x4*)(scp + 32 * eh + 8 * gq + 4 * hi);
;                 u32x2 wv; wv.x = pk2(acc[eh][4 * gq] * sc.x, acc[eh][4 * gq + 1] * sc.y); wv.y = pk2(acc[eh][4 * gq + 2] * sc.z, acc[eh][4 * gq + 3] * sc.w);
;                 *(u32x2*)(yr + 32 * eh + 8 * gq) = wv;
;             }
	v_add_f32_e32 v26, 0, v12
	v_add_f32_e32 v26, v11, v26
	v_cndmask_b32_e64 v28, v10, 0, s[0:1]
	v_add_f32_e32 v26, v28, v26
	v_add_f32_e32 v26, v27, v26
	v_cndmask_b32_e32 v16, 0, v16, vcc
	v_add_f32_e32 v26, v16, v26
	v_add_f32_e32 v26, v9, v26
	v_add_f32_e32 v26, v29, v26
	v_add_f32_e32 v26, v30, v26
	v_cndmask_b32_e64 v14, 0, v14, s[2:3]
	v_add_f32_e32 v26, v14, v26
	v_add_f32_e32 v26, v19, v26
	v_add_f32_e32 v26, v18, v26
	v_add_f32_e32 v26, v21, v26
	v_add_f32_e32 v26, v20, v26
	v_add_f32_e32 v26, v23, v26
	v_add_f32_e32 v26, v22, v26
	v_add_f32_e32 v25, v25, v26
	v_fma_f32 v24, v64, v24, -v11
	v_fma_f32 v25, v64, v25, -v12
	ds_write2st64_b32 v72, v24, v25 offset0:112 offset1:116
	v_add_f32_e32 v24, 0, v13
	v_add_f32_e32 v24, v12, v24
	v_cndmask_b32_e64 v11, v11, 0, s[0:1]
	v_add_f32_e32 v24, v11, v24
	v_add_f32_e32 v24, v28, v24
	v_cndmask_b32_e32 v17, 0, v17, vcc
	v_add_f32_e32 v24, v17, v24
	v_add_f32_e32 v24, v16, v24
	v_add_f32_e32 v24, v9, v24
	v_add_f32_e32 v24, v29, v24
	v_cndmask_b32_e64 v15, 0, v15, s[2:3]
	v_add_f32_e32 v24, v15, v24
	v_add_f32_e32 v24, v14, v24
	v_add_f32_e32 v24, v19, v24
	v_add_f32_e32 v24, v18, v24
	v_add_f32_e32 v24, v21, v24
	v_add_f32_e32 v24, v20, v24
	v_add_f32_e32 v24, v23, v24
	v_add_f32_e32 v22, v22, v24
	v_add_f32_e32 v24, 0, v70
	v_fma_f32 v22, v64, v22, -v13
	v_add_f32_e32 v13, v13, v24
	v_cndmask_b32_e64 v12, v12, 0, s[0:1]
	v_add_f32_e32 v12, v12, v13
	v_add_f32_e32 v11, v11, v12
	v_cndmask_b32_e32 v10, 0, v10, vcc
	v_add_f32_e32 v10, v10, v11
	v_add_f32_e32 v10, v17, v10
	v_add_f32_e32 v10, v16, v10
	v_add_f32_e32 v9, v9, v10
	v_cndmask_b32_e64 v8, 0, v8, s[2:3]
	v_add_f32_e32 v8, v8, v9
	v_add_f32_e32 v8, v15, v8
	v_add_f32_e32 v8, v14, v8
	v_add_f32_e32 v8, v19, v8
	v_add_f32_e32 v8, v18, v8
	v_add_f32_e32 v8, v21, v8
	v_add_f32_e32 v8, v20, v8
	v_add_f32_e32 v8, v23, v8
	v_fma_f32 v8, v64, v8, -v70
	v_and_b32_e32 v70, 0xc0, v68
	ds_write2st64_b32 v72, v22, v8 offset0:120 offset1:124
	v_lshl_add_u32 v8, v67, 10, s19
	v_lshlrev_b32_e32 v64, 2, v70
	v_and_b32_e32 v9, 32, v68
	v_add3_u32 v65, v8, v64, v9
	s_waitcnt lgkmcnt(0)
	s_barrier
	ds_read_b128 v[8:11], v65
	ds_read_b128 v[12:15], v65 offset:16
	ds_read_b128 v[56:59], v65 offset:64
	ds_read_b128 v[60:63], v65 offset:80
	s_not_b32 s2, s18
	v_mov_b32_e32 v68, 0
	s_waitcnt lgkmcnt(3)
	v_cvt_pk_bf16_f32 v8, v8, v9
	v_cvt_pk_bf16_f32 v9, v10, v11
	s_waitcnt lgkmcnt(2)
	v_cvt_pk_bf16_f32 v10, v12, v13
	v_cvt_pk_bf16_f32 v11, v14, v15
	s_waitcnt lgkmcnt(1)
	v_cvt_pk_bf16_f32 v56, v56, v57
	v_cvt_pk_bf16_f32 v57, v58, v59
	v_mfma_f32_32x32x16_bf16 v[16:31], v[0:3], v[8:11], 0
	s_waitcnt lgkmcnt(0)
	v_cvt_pk_bf16_f32 v58, v60, v61
	v_cvt_pk_bf16_f32 v59, v62, v63
	v_mov_b32_e32 v60, 0
	v_mov_b32_e32 v71, 0
	v_mfma_f32_32x32x16_bf16 v[0:15], v[4:7], v[8:11], 0
	v_mfma_f32_32x32x16_bf16 v[16:31], v[32:35], v[56:59], v[16:31]
	v_mfma_f32_32x32x16_bf16 v[0:15], v[44:47], v[56:59], v[0:15]
	ds_read_b128 v[32:35], v65 offset:128
	ds_read_b128 v[44:47], v65 offset:144
	s_waitcnt lgkmcnt(1)
	v_cvt_pk_bf16_f32 v32, v32, v33
	v_cvt_pk_bf16_f32 v33, v34, v35
	s_waitcnt lgkmcnt(0)
	v_cvt_pk_bf16_f32 v34, v44, v45
	v_cvt_pk_bf16_f32 v35, v46, v47
	s_nop 1
	v_mfma_f32_32x32x16_bf16 v[16:31], v[36:39], v[32:35], v[16:31]
	v_mfma_f32_32x32x16_bf16 v[0:15], v[48:51], v[32:35], v[0:15]
	ds_read_b128 v[32:35], v65 offset:192
	ds_read_b128 v[36:39], v65 offset:208
	v_mov_b32_e32 v65, v129
	s_waitcnt lgkmcnt(1)
	v_cvt_pk_bf16_f32 v32, v32, v33
	v_cvt_pk_bf16_f32 v33, v34, v35
	s_waitcnt lgkmcnt(0)
	v_cvt_pk_bf16_f32 v34, v36, v37
	v_cvt_pk_bf16_f32 v35, v38, v39
	v_lshlrev_b32_e32 v36, 1, v70
	v_mov_b32_e32 v37, v129
	v_mfma_f32_32x32x16_bf16 v[16:31], v[40:43], v[32:35], v[16:31]
	v_mov_b32_e32 v70, 0
	v_mfma_f32_32x32x16_bf16 v[0:15], v[52:55], v[32:35], v[0:15]
	v_or_b32_e32 v32, s17, v67
	v_ashrrev_i32_e32 v33, 31, v32
	v_lshlrev_b64 v[32:33], 11, v[32:33]
	v_lshl_add_u64 v[32:33], s[88:89], 0, v[32:33]
	v_lshl_add_u64 v[32:33], v[32:33], 0, v[36:37]
	v_lshlrev_b32_e32 v36, 3, v69
	v_lshl_add_u64 v[34:35], s[12:13], 0, v[64:65]
	v_lshl_add_u64 v[32:33], v[32:33], 0, v[36:37]
	v_lshlrev_b32_e32 v36, 4, v69
	v_lshl_add_u64 v[34:35], v[34:35], 0, v[36:37]
	global_load_dwordx4 v[36:39], v[34:35], off
	global_load_dwordx4 v[40:43], v[34:35], off offset:32
	global_load_dwordx4 v[44:47], v[34:35], off offset:64
	global_load_dwordx4 v[48:51], v[34:35], off offset:96
	global_load_dwordx4 v[52:55], v[34:35], off offset:128
	v_mov_b32_e32 v64, 0
	v_mov_b32_e32 v65, 0
	v_mov_b32_e32 v67, 0
	v_mov_b32_e32 v69, 0
	s_waitcnt vmcnt(0)
	v_pk_mul_f32 v[36:37], v[16:17], v[36:37]
	v_pk_mul_f32 v[38:39], v[18:19], v[38:39]
	v_cvt_pk_bf16_f32 v36, v36, v37
	v_cvt_pk_bf16_f32 v37, v38, v39
	global_store_dwordx2 v[32:33], v[36:37], off offset:512
	global_load_dwordx4 v[36:39], v[34:35], off offset:160
	v_pk_mul_f32 v[40:41], v[20:21], v[40:41]
	v_pk_mul_f32 v[42:43], v[22:23], v[42:43]
	v_cvt_pk_bf16_f32 v40, v40, v41
	v_cvt_pk_bf16_f32 v41, v42, v43
	global_store_dwordx2 v[32:33], v[40:41], off offset:528
	global_load_dwordx4 v[40:43], v[34:35], off offset:192
	v_pk_mul_f32 v[44:45], v[24:25], v[44:45]
	v_pk_mul_f32 v[46:47], v[26:27], v[46:47]
	v_cvt_pk_bf16_f32 v44, v44, v45
	v_cvt_pk_bf16_f32 v45, v46, v47
	global_store_dwordx2 v[32:33], v[44:45], off offset:544
	global_load_dwordx4 v[44:47], v[34:35], off offset:224
	v_pk_mul_f32 v[48:49], v[28:29], v[48:49]
	v_pk_mul_f32 v[50:51], v[30:31], v[50:51]
	v_cvt_pk_bf16_f32 v48, v48, v49
	v_cvt_pk_bf16_f32 v49, v50, v51
	global_store_dwordx2 v[32:33], v[48:49], off offset:560
	v_pk_mul_f32 v[52:53], v[0:1], v[52:53]
	v_pk_mul_f32 v[54:55], v[2:3], v[54:55]
	v_cvt_pk_bf16_f32 v52, v52, v53
	v_cvt_pk_bf16_f32 v53, v54, v55
	global_store_dwordx2 v[32:33], v[52:53], off offset:576
	s_waitcnt vmcnt(0)
	v_pk_mul_f32 v[36:37], v[4:5], v[36:37]
	v_pk_mul_f32 v[38:39], v[6:7], v[38:39]
	v_cvt_pk_bf16_f32 v36, v36, v37
	v_cvt_pk_bf16_f32 v37, v38, v39
	global_store_dwordx2 v[32:33], v[36:37], off offset:592
	v_pk_mul_f32 v[40:41], v[8:9], v[40:41]
	v_pk_mul_f32 v[42:43], v[10:11], v[42:43]
	v_cvt_pk_bf16_f32 v40, v40, v41
	v_cvt_pk_bf16_f32 v41, v42, v43
	global_store_dwordx2 v[32:33], v[40:41], off offset:608
	v_pk_mul_f32 v[44:45], v[12:13], v[44:45]
	v_pk_mul_f32 v[46:47], v[14:15], v[46:47]
	v_cvt_pk_bf16_f32 v44, v44, v45
	v_cvt_pk_bf16_f32 v45, v46, v47
	global_store_dwordx2 v[32:33], v[44:45], off offset:624
	v_lshlrev_b32_e32 v0, 2, v66
	v_add_u32_e32 v1, -2, v0
	v_cmp_lt_i32_e32 vcc, s2, v1
	v_add_u32_e32 v96, s17, v1
	v_mov_b32_e32 v66, 0
	s_barrier
	s_and_saveexec_b64 s[0:1], vcc
	s_cbranch_execz .LBB0_180
	v_mad_i64_i32 v[2:3], s[18:19], v96, s70, v[88:89]
	global_load_dwordx4 v[64:67], v[2:3], off offset:1536
	global_load_dwordx4 v[68:71], v[2:3], off offset:2560
